# P5 mid hook and final epilogue: full vmcnt(0) replaced by counted waits at first consumers
# speedup vs baseline: 1.0021x; 1.0021x over previous
.Lpk1350_seg3:
	s_add_i32 s59, 0, 0x18000
	s_add_i32 s61, 0, 0x1c000
	v_add_u32_e32 v180, s59, v175
	v_add_u32_e32 v181, s61, v175
	ds_read_b128 v[136:139], v180
	ds_read_b128 v[140:143], v180 offset:1024
	ds_read_b128 v[144:147], v180 offset:2048
	ds_read_b128 v[148:151], v180 offset:3072
	ds_read_b128 v[182:185], v181
	ds_read_b128 v[186:189], v181 offset:1024
	ds_read_b128 v[190:193], v181 offset:2048
	ds_read_b128 v[194:197], v181 offset:3072
	s_mov_b32 m0, s41
	v_lshl_add_u64 v[238:239], v[230:231], 0, s[14:15]
	ds_read_b128 v[198:201], v179 offset:32768
	ds_read_b128 v[202:205], v179 offset:33792
	ds_read_b128 v[206:209], v179 offset:34816
	ds_read_b128 v[210:213], v179 offset:35840
	ds_read_b128 v[214:217], v179 offset:36864
	ds_read_b128 v[218:221], v179 offset:37888
	ds_read_b128 v[222:225], v179 offset:38912
	ds_read_b128 v[226:229], v179 offset:39936
	global_load_lds_dwordx4 v[238:239], off
	v_lshl_add_u64 v[238:239], v[232:233], 0, s[14:15]
	s_mov_b32 m0, s42
	s_nop 0
	global_load_lds_dwordx4 v[238:239], off
	s_waitcnt vmcnt(8)
	s_waitcnt lgkmcnt(0)
	s_setprio 1
	s_barrier
	v_mfma_f32_16x16x32_bf16 v[124:127], v[136:139], v[198:201], v[124:127]
	v_mfma_f32_16x16x32_bf16 v[120:123], v[144:147], v[198:201], v[120:123]
	v_mfma_f32_16x16x32_bf16 v[116:119], v[136:139], v[206:209], v[116:119]
	v_mfma_f32_16x16x32_bf16 v[112:115], v[144:147], v[206:209], v[112:115]
	v_mfma_f32_16x16x32_bf16 v[104:107], v[136:139], v[214:217], v[104:107]
	v_mfma_f32_16x16x32_bf16 v[96:99], v[144:147], v[214:217], v[96:99]
	v_mfma_f32_16x16x32_bf16 v[84:87], v[136:139], v[222:225], v[84:87]
	v_mfma_f32_16x16x32_bf16 v[80:83], v[144:147], v[222:225], v[80:83]
	v_mfma_f32_16x16x32_bf16 v[124:127], v[140:143], v[202:205], v[124:127]
	v_mfma_f32_16x16x32_bf16 v[120:123], v[148:151], v[202:205], v[120:123]
	v_mfma_f32_16x16x32_bf16 v[116:119], v[140:143], v[210:213], v[116:119]
	v_mfma_f32_16x16x32_bf16 v[112:115], v[148:151], v[210:213], v[112:115]
	v_mfma_f32_16x16x32_bf16 v[104:107], v[140:143], v[218:221], v[104:107]
	v_mfma_f32_16x16x32_bf16 v[96:99], v[148:151], v[218:221], v[96:99]
	v_mfma_f32_16x16x32_bf16 v[84:87], v[140:143], v[226:229], v[84:87]
	v_mfma_f32_16x16x32_bf16 v[80:83], v[148:151], v[226:229], v[80:83]
	s_setprio 0
	s_setprio 1
	v_mfma_f32_16x16x32_bf16 v[108:111], v[182:185], v[198:201], v[108:111]
	v_mfma_f32_16x16x32_bf16 v[100:103], v[190:193], v[198:201], v[100:103]
	v_mfma_f32_16x16x32_bf16 v[92:95], v[182:185], v[206:209], v[92:95]
	v_mfma_f32_16x16x32_bf16 v[88:91], v[190:193], v[206:209], v[88:91]
	v_mfma_f32_16x16x32_bf16 v[76:79], v[182:185], v[214:217], v[76:79]
	v_mfma_f32_16x16x32_bf16 v[72:75], v[190:193], v[214:217], v[72:75]
	v_mfma_f32_16x16x32_bf16 v[68:71], v[182:185], v[222:225], v[68:71]
	v_mfma_f32_16x16x32_bf16 v[64:67], v[190:193], v[222:225], v[64:67]
	v_mfma_f32_16x16x32_bf16 v[108:111], v[186:189], v[202:205], v[108:111]
	v_mfma_f32_16x16x32_bf16 v[100:103], v[194:197], v[202:205], v[100:103]
	v_mfma_f32_16x16x32_bf16 v[92:95], v[186:189], v[210:213], v[92:95]
	v_mfma_f32_16x16x32_bf16 v[88:91], v[194:197], v[210:213], v[88:91]
	v_mfma_f32_16x16x32_bf16 v[76:79], v[186:189], v[218:221], v[76:79]
	v_mfma_f32_16x16x32_bf16 v[72:75], v[194:197], v[218:221], v[72:75]
	v_mfma_f32_16x16x32_bf16 v[68:71], v[186:189], v[226:229], v[68:71]
	v_mfma_f32_16x16x32_bf16 v[64:67], v[194:197], v[226:229], v[64:67]
	s_barrier
	s_setprio 0
	s_add_i32 s59, s59, s38
	v_lshl_add_u64 v[238:239], v[234:235], 0, s[16:17]
	s_mov_b32 m0, s59
	s_add_i32 s60, s59, 0x2000
	ds_read_b128 v[198:201], v179 offset:49152
	ds_read_b128 v[202:205], v179 offset:50176
	global_load_lds_dwordx4 v[238:239], off
	v_lshl_add_u64 v[238:239], v[236:237], 0, s[16:17]
	s_mov_b32 m0, s60
	s_add_i32 s61, s61, s38
	ds_read_b128 v[206:209], v179 offset:51200
	ds_read_b128 v[210:213], v179 offset:52224
	global_load_lds_dwordx4 v[238:239], off
	v_lshl_add_u64 v[234:235], v[234:235], 0, s[18:19]
	s_mov_b32 m0, s61
	s_add_i32 s62, s61, 0x2000
	ds_read_b128 v[214:217], v179 offset:53248
	global_load_lds_dwordx4 v[234:235], off
	v_lshl_add_u64 v[234:235], v[236:237], 0, s[18:19]
	s_mov_b32 m0, s62
	v_lshl_add_u64 v[230:231], v[230:231], 0, s[16:17]
	ds_read_b128 v[218:221], v179 offset:54272
	global_load_lds_dwordx4 v[234:235], off
	s_mov_b32 m0, s44
	ds_read_b128 v[222:225], v179 offset:55296
	global_load_lds_dwordx4 v[230:231], off
	v_lshl_add_u64 v[230:231], v[232:233], 0, s[16:17]
	s_mov_b32 m0, s45
	ds_read_b128 v[226:229], v179 offset:56320
	global_load_lds_dwordx4 v[230:231], off
	s_waitcnt vmcnt(8)
	s_waitcnt lgkmcnt(0)
	s_setprio 1
	s_barrier
; __device__ __forceinline__ unsigned cvt_pk_bf16(float lo, float hi) { unsigned r; asm volatile("v_cvt_pk_bf16_f32 %0, %1, %2" : "=v"(r) : "v"(lo), "v"(hi)); return r; }
; __device__ __forceinline__ float bflo(unsigned w) { return __uint_as_float(w << 16); }
; __device__ __forceinline__ float bfhi(unsigned w) { return __uint_as_float(w & 0xffff0000u); }
;     __device__ __forceinline__ void scale(Acc& acc, const Unit& u, int wr, int wc, int fr, int fq, int pc, bool store) const {
;     ...
;         for (int ai = 0; ai < 2; ++ai) {
;             u32x4 g[4][2];
; #pragma unroll
;             for (int m = 0; m < 4; ++m) {
;                 const unsigned rowoff = (unsigned)(row0 + ai * HALF + m * 16) * (unsigned)(NIN * 2) + (unsigned)col0 * 2u;
; #pragma unroll
;                 for (int bj = 0; bj < 2; ++bj) g[m][bj] = *(const u32x4*)(Pb + (rowoff + (unsigned)((pc + bj * HALF) * 2)));
;             }
; #pragma unroll
;             for (int m = 0; m < 4; ++m) {
;                 const unsigned ooff = (unsigned)(row0 + ai * HALF + m * 16) * (unsigned)(ldo * 2) + (unsigned)col0 * 2u;
; #pragma unroll
;                 for (int bj = 0; bj < 2; ++bj) {
;                     const u32x4 gg = g[m][bj];
;                     const f32x4 s0 = (f32x4){bflo(gg.x), bfhi(gg.x), bflo(gg.y), bfhi(gg.y)}, s1 = (f32x4){bflo(gg.z), bfhi(gg.z), bflo(gg.w), bfhi(gg.w)};
;                     const f32x4 v0 = acc[ai][bj][m][0] * s0, v1 = acc[ai][bj][m][1] * s1;
;                     if (store) { u32x4 w; w.x = cvt_pk_bf16(v0[0], v0[1]); w.y = cvt_pk_bf16(v0[2], v0[3]); w.z = cvt_pk_bf16(v1[0], v1[1]); w.w = cvt_pk_bf16(v1[2], v1[3]); *(u32x4*)(Ob + (ooff + (unsigned)(bj * HALF * 2))) = w; }
;                     else { acc[ai][bj][m][0] = v0; acc[ai][bj][m][1] = v1; }
	v_mfma_f32_16x16x32_bf16 v[60:63], v[136:139], v[198:201], v[60:63]
	v_mfma_f32_16x16x32_bf16 v[56:59], v[144:147], v[198:201], v[56:59]
	v_mfma_f32_16x16x32_bf16 v[48:51], v[136:139], v[206:209], v[48:51]
	v_mfma_f32_16x16x32_bf16 v[40:43], v[144:147], v[206:209], v[40:43]
	v_mfma_f32_16x16x32_bf16 v[32:35], v[136:139], v[214:217], v[32:35]
	v_mfma_f32_16x16x32_bf16 v[24:27], v[144:147], v[214:217], v[24:27]
	v_mfma_f32_16x16x32_bf16 v[16:19], v[136:139], v[222:225], v[16:19]
	v_mfma_f32_16x16x32_bf16 v[8:11], v[144:147], v[222:225], v[8:11]
	v_mfma_f32_16x16x32_bf16 v[60:63], v[140:143], v[202:205], v[60:63]
	v_mfma_f32_16x16x32_bf16 v[56:59], v[148:151], v[202:205], v[56:59]
	v_mfma_f32_16x16x32_bf16 v[48:51], v[140:143], v[210:213], v[48:51]
	v_mfma_f32_16x16x32_bf16 v[40:43], v[148:151], v[210:213], v[40:43]
	v_mfma_f32_16x16x32_bf16 v[32:35], v[140:143], v[218:221], v[32:35]
	v_mfma_f32_16x16x32_bf16 v[24:27], v[148:151], v[218:221], v[24:27]
	v_mfma_f32_16x16x32_bf16 v[16:19], v[140:143], v[226:229], v[16:19]
	v_mfma_f32_16x16x32_bf16 v[8:11], v[148:151], v[226:229], v[8:11]
	s_setprio 0
	s_setprio 1
	v_mfma_f32_16x16x32_bf16 v[52:55], v[182:185], v[198:201], v[52:55]
	v_mfma_f32_16x16x32_bf16 v[44:47], v[190:193], v[198:201], v[44:47]
	v_mfma_f32_16x16x32_bf16 v[36:39], v[182:185], v[206:209], v[36:39]
	v_mfma_f32_16x16x32_bf16 v[28:31], v[190:193], v[206:209], v[28:31]
	v_mfma_f32_16x16x32_bf16 v[20:23], v[182:185], v[214:217], v[20:23]
	v_mfma_f32_16x16x32_bf16 v[12:15], v[190:193], v[214:217], v[12:15]
	v_mfma_f32_16x16x32_bf16 v[4:7], v[182:185], v[222:225], v[4:7]
	v_mfma_f32_16x16x32_bf16 v[0:3], v[190:193], v[222:225], v[0:3]
	v_mfma_f32_16x16x32_bf16 v[52:55], v[186:189], v[202:205], v[52:55]
	v_mfma_f32_16x16x32_bf16 v[44:47], v[194:197], v[202:205], v[44:47]
	v_mfma_f32_16x16x32_bf16 v[36:39], v[186:189], v[210:213], v[36:39]
	v_mfma_f32_16x16x32_bf16 v[28:31], v[194:197], v[210:213], v[28:31]
	v_mfma_f32_16x16x32_bf16 v[20:23], v[186:189], v[218:221], v[20:23]
	v_mfma_f32_16x16x32_bf16 v[12:15], v[194:197], v[218:221], v[12:15]
	v_mfma_f32_16x16x32_bf16 v[4:7], v[186:189], v[226:229], v[4:7]
	v_mfma_f32_16x16x32_bf16 v[0:3], v[194:197], v[226:229], v[0:3]
	s_barrier
	s_setprio 0
	s_add_i32 s21, s21, 2
	s_add_u32 s28, s28, 0x100
	s_addc_u32 s29, s29, 0
	s_cmp_gt_u32 s21, 5
	s_cbranch_scc0 .LBB0_1350
	v_lshl_add_u32 v182, s34, 8, v174
	v_lshl_or_b32 v183, s23, 8, v176
	v_mov_b32_e32 v128, v182
	v_mov_b32_e32 v129, v183
	s_ashr_i32 s23, s22, 31
	v_mul_lo_u32 v128, v128, s52
	v_lshl_add_u32 v228, v129, 1, v128
	v_add_u32_e32 v128, 0x1200, v228
	v_add_u32_e32 v140, 0x49200, v228
	global_load_dwordx4 v[148:151], v128, s[68:69]
	global_load_dwordx4 v[144:147], v140, s[68:69]
	v_add_u32_e32 v128, 0x1300, v228
	v_add_u32_e32 v140, 0x49300, v228
	global_load_dwordx4 v[136:139], v128, s[68:69]
	v_add_u32_e32 v184, 0x6d200, v228
	global_load_dwordx4 v[140:143], v140, s[68:69]
	v_add_u32_e32 v128, 0x25200, v228
	global_load_dwordx4 v[132:135], v128, s[68:69]
	v_add_u32_e32 v128, 0x25300, v228
	global_load_dwordx4 v[128:131], v128, s[68:69]
	v_add_u32_e32 v188, 0x6d300, v228
	global_load_dwordx4 v[184:187], v184, s[68:69]
	s_nop 0
	global_load_dwordx4 v[188:191], v188, s[68:69]
	v_add_u32_e32 v192, 0x121200, v228
	v_add_u32_e32 v196, 0x121300, v228
	global_load_dwordx4 v[192:195], v192, s[68:69]
	s_nop 0
	global_load_dwordx4 v[196:199], v196, s[68:69]
	s_ashr_i32 s21, s20, 31
	s_lshl_b64 s[28:29], s[22:23], 19
	s_lshl_b64 s[30:31], s[20:21], 19
	s_add_u32 s28, s1, s28
	s_addc_u32 s29, s33, s29
	s_add_u32 s30, s36, s30
	s_addc_u32 s31, s37, s31
	s_and_b64 s[34:35], s[2:3], exec
	s_cselect_b32 s21, s29, s27
	s_cselect_b32 s23, s28, s26
	s_cselect_b32 s63, s31, s25
	s_cselect_b32 s66, s30, s24
	s_add_u32 s26, s26, 0x40480
	s_addc_u32 s27, s27, 0
	s_add_u32 s67, s24, 0x500
	s_addc_u32 s70, s25, 0
	s_mov_b32 s71, 6
	s_waitcnt vmcnt(9)
	v_lshlrev_b32_e32 v200, 16, v148
	v_and_b32_e32 v201, 0xffff0000, v148
	v_lshlrev_b32_e32 v148, 16, v149
	v_and_b32_e32 v149, 0xffff0000, v149
	s_waitcnt vmcnt(7)
	v_lshlrev_b32_e32 v204, 16, v136
	v_and_b32_e32 v205, 0xffff0000, v136
	v_lshlrev_b32_e32 v206, 16, v137
	v_and_b32_e32 v207, 0xffff0000, v137
	v_lshlrev_b32_e32 v202, 16, v150
	v_and_b32_e32 v203, 0xffff0000, v150
	s_waitcnt vmcnt(4)
	v_lshlrev_b32_e32 v224, 16, v130
	v_and_b32_e32 v225, 0xffff0000, v130
	v_lshlrev_b32_e32 v226, 16, v131
	v_and_b32_e32 v227, 0xffff0000, v131
	v_lshlrev_b32_e32 v150, 16, v151
	v_and_b32_e32 v151, 0xffff0000, v151
	v_lshlrev_b32_e32 v208, 16, v138
	v_and_b32_e32 v209, 0xffff0000, v138
	v_lshlrev_b32_e32 v210, 16, v139
	v_and_b32_e32 v211, 0xffff0000, v139
	v_pk_mul_f32 v[138:139], v[126:127], v[148:149]
	v_pk_mul_f32 v[136:137], v[124:125], v[200:201]
	v_pk_mul_f32 v[126:127], v[110:111], v[206:207]
	v_pk_mul_f32 v[124:125], v[108:109], v[204:205]
	v_pk_mul_f32 v[110:111], v[90:91], v[226:227]
	v_pk_mul_f32 v[108:109], v[88:89], v[224:225]
	v_lshlrev_b32_e32 v88, 16, v144
	v_and_b32_e32 v89, 0xffff0000, v144
	v_add_u32_e32 v91, 0x145200, v228
	v_lshlrev_b32_e32 v212, 16, v132
	v_and_b32_e32 v213, 0xffff0000, v132
	v_lshlrev_b32_e32 v214, 16, v133
	v_and_b32_e32 v215, 0xffff0000, v133
	v_lshlrev_b32_e32 v216, 16, v134
	v_and_b32_e32 v217, 0xffff0000, v134
	v_lshlrev_b32_e32 v218, 16, v135
	v_and_b32_e32 v219, 0xffff0000, v135
	v_lshlrev_b32_e32 v222, 16, v129
	v_and_b32_e32 v223, 0xffff0000, v129
	v_pk_mul_f32 v[134:135], v[122:123], v[150:151]
	v_pk_mul_f32 v[132:133], v[120:121], v[202:203]
	v_pk_mul_f32 v[120:121], v[100:101], v[208:209]
	v_lshlrev_b32_e32 v90, 16, v145
	global_load_dwordx4 v[148:151], v91, s[68:69]
	v_and_b32_e32 v91, 0xffff0000, v145
	v_pk_mul_f32 v[100:101], v[104:105], v[88:89]
	v_add_u32_e32 v89, 0x145300, v228
	v_pk_mul_f32 v[122:123], v[102:103], v[210:211]
	v_pk_mul_f32 v[130:131], v[118:119], v[214:215]
	v_pk_mul_f32 v[118:119], v[114:115], v[218:219]
	v_pk_mul_f32 v[114:115], v[94:95], v[222:223]
	v_lshlrev_b32_e32 v94, 16, v147
	v_and_b32_e32 v95, 0xffff0000, v147
	v_pk_mul_f32 v[102:103], v[106:107], v[90:91]
	v_lshlrev_b32_e32 v88, 16, v140
	global_load_dwordx4 v[104:107], v89, s[68:69]
	v_and_b32_e32 v89, 0xffff0000, v140
	v_lshlrev_b32_e32 v90, 16, v141
	v_and_b32_e32 v91, 0xffff0000, v141
	v_lshlrev_b32_e32 v140, 16, v143
	v_and_b32_e32 v141, 0xffff0000, v143
	v_lshlrev_b32_e32 v220, 16, v128
	v_and_b32_e32 v221, 0xffff0000, v128
	v_pk_mul_f32 v[98:99], v[98:99], v[94:95]
	v_pk_mul_f32 v[94:95], v[78:79], v[90:91]
	v_pk_mul_f32 v[90:91], v[74:75], v[140:141]
	v_add_u32_e32 v74, 0x169200, v228
	v_pk_mul_f32 v[128:129], v[116:117], v[212:213]
	v_pk_mul_f32 v[116:117], v[112:113], v[216:217]
	v_pk_mul_f32 v[112:113], v[92:93], v[220:221]
	v_lshlrev_b32_e32 v92, 16, v146
	v_and_b32_e32 v93, 0xffff0000, v146
	v_lshlrev_b32_e32 v144, 16, v142
	v_and_b32_e32 v145, 0xffff0000, v142
	global_load_dwordx4 v[140:143], v74, s[68:69]
	s_waitcnt vmcnt(6)
; __device__ __forceinline__ unsigned cvt_pk_bf16(float lo, float hi) { unsigned r; asm volatile("v_cvt_pk_bf16_f32 %0, %1, %2" : "=v"(r) : "v"(lo), "v"(hi)); return r; }
; __device__ __forceinline__ float bflo(unsigned w) { return __uint_as_float(w << 16); }
; __device__ __forceinline__ float bfhi(unsigned w) { return __uint_as_float(w & 0xffff0000u); }
;     __device__ __forceinline__ void scale(Acc& acc, const Unit& u, int wr, int wc, int fr, int fq, int pc, bool store) const {
;     ...
;         for (int ai = 0; ai < 2; ++ai) {
;             u32x4 g[4][2];
; #pragma unroll
;             for (int m = 0; m < 4; ++m) {
;                 const unsigned rowoff = (unsigned)(row0 + ai * HALF + m * 16) * (unsigned)(NIN * 2) + (unsigned)col0 * 2u;
; #pragma unroll
;                 for (int bj = 0; bj < 2; ++bj) g[m][bj] = *(const u32x4*)(Pb + (rowoff + (unsigned)((pc + bj * HALF) * 2)));
;             }
; #pragma unroll
;             for (int m = 0; m < 4; ++m) {
;                 const unsigned ooff = (unsigned)(row0 + ai * HALF + m * 16) * (unsigned)(ldo * 2) + (unsigned)col0 * 2u;
; #pragma unroll
;                 for (int bj = 0; bj < 2; ++bj) {
;                     const u32x4 gg = g[m][bj];
;                     const f32x4 s0 = (f32x4){bflo(gg.x), bfhi(gg.x), bflo(gg.y), bfhi(gg.y)}, s1 = (f32x4){bflo(gg.z), bfhi(gg.z), bflo(gg.w), bfhi(gg.w)};
;                     const f32x4 v0 = acc[ai][bj][m][0] * s0, v1 = acc[ai][bj][m][1] * s1;
;                     if (store) { u32x4 w; w.x = cvt_pk_bf16(v0[0], v0[1]); w.y = cvt_pk_bf16(v0[2], v0[3]); w.z = cvt_pk_bf16(v1[0], v1[1]); w.w = cvt_pk_bf16(v1[2], v1[3]); *(u32x4*)(Ob + (ooff + (unsigned)(bj * HALF * 2))) = w; }
;                     else { acc[ai][bj][m][0] = v0; acc[ai][bj][m][1] = v1; }
	v_lshlrev_b32_e32 v74, 16, v185
	v_and_b32_e32 v75, 0xffff0000, v185
	v_pk_mul_f32 v[96:97], v[96:97], v[92:93]
	v_pk_mul_f32 v[92:93], v[76:77], v[88:89]
	v_pk_mul_f32 v[88:89], v[72:73], v[144:145]
	v_lshlrev_b32_e32 v72, 16, v184
	v_and_b32_e32 v73, 0xffff0000, v184
	v_lshlrev_b32_e32 v76, 16, v186
	v_and_b32_e32 v77, 0xffff0000, v186
	v_pk_mul_f32 v[86:87], v[86:87], v[74:75]
	v_add_u32_e32 v74, 0x169300, v228
	v_lshlrev_b32_e32 v78, 16, v187
	v_and_b32_e32 v79, 0xffff0000, v187
	global_load_dwordx4 v[144:147], v74, s[68:69]
	v_pk_mul_f32 v[84:85], v[84:85], v[72:73]
	v_pk_mul_f32 v[76:77], v[80:81], v[76:77]
	s_waitcnt vmcnt(6)
	v_lshlrev_b32_e32 v72, 16, v188
	v_and_b32_e32 v73, 0xffff0000, v188
	v_lshlrev_b32_e32 v184, 16, v190
	v_and_b32_e32 v185, 0xffff0000, v190
	v_add_u32_e32 v80, 0x18d200, v228
	v_pk_mul_f32 v[78:79], v[82:83], v[78:79]
	v_lshlrev_b32_e32 v74, 16, v189
	v_and_b32_e32 v75, 0xffff0000, v189
	v_lshlrev_b32_e32 v186, 16, v191
	global_load_dwordx4 v[80:83], v80, s[68:69]
	v_and_b32_e32 v187, 0xffff0000, v191
	v_pk_mul_f32 v[72:73], v[68:69], v[72:73]
	v_pk_mul_f32 v[68:69], v[64:65], v[184:185]
	v_add_u32_e32 v64, 0x18d300, v228
	v_pk_mul_f32 v[74:75], v[70:71], v[74:75]
	v_pk_mul_f32 v[70:71], v[66:67], v[186:187]
	global_load_dwordx4 v[184:187], v64, s[68:69]
	s_waitcnt vmcnt(7)
	v_lshlrev_b32_e32 v64, 16, v192
	v_and_b32_e32 v65, 0xffff0000, v192
	v_lshlrev_b32_e32 v66, 16, v193
	v_and_b32_e32 v67, 0xffff0000, v193
	v_lshlrev_b32_e32 v188, 16, v194
	v_and_b32_e32 v189, 0xffff0000, v194
	v_lshlrev_b32_e32 v190, 16, v195
	v_and_b32_e32 v191, 0xffff0000, v195
	v_pk_mul_f32 v[62:63], v[62:63], v[66:67]
	v_pk_mul_f32 v[60:61], v[60:61], v[64:65]
	v_pk_mul_f32 v[66:67], v[58:59], v[190:191]
	v_pk_mul_f32 v[64:65], v[56:57], v[188:189]
	s_waitcnt vmcnt(6)
	v_lshlrev_b32_e32 v56, 16, v196
	v_and_b32_e32 v57, 0xffff0000, v196
	v_lshlrev_b32_e32 v58, 16, v197
	v_and_b32_e32 v59, 0xffff0000, v197
	v_lshlrev_b32_e32 v188, 16, v198
	v_and_b32_e32 v189, 0xffff0000, v198
	v_lshlrev_b32_e32 v190, 16, v199
	v_and_b32_e32 v191, 0xffff0000, v199
	v_pk_mul_f32 v[54:55], v[54:55], v[58:59]
	v_pk_mul_f32 v[52:53], v[52:53], v[56:57]
	v_pk_mul_f32 v[58:59], v[46:47], v[190:191]
	v_pk_mul_f32 v[56:57], v[44:45], v[188:189]
	s_waitcnt vmcnt(5)
	v_lshlrev_b32_e32 v44, 16, v148
	v_and_b32_e32 v45, 0xffff0000, v148
	v_lshlrev_b32_e32 v46, 16, v149
	v_and_b32_e32 v47, 0xffff0000, v149
	v_lshlrev_b32_e32 v148, 16, v150
	v_and_b32_e32 v149, 0xffff0000, v150
	v_lshlrev_b32_e32 v150, 16, v151
	v_and_b32_e32 v151, 0xffff0000, v151
	v_pk_mul_f32 v[46:47], v[50:51], v[46:47]
	v_pk_mul_f32 v[44:45], v[48:49], v[44:45]
	v_pk_mul_f32 v[50:51], v[42:43], v[150:151]
	v_pk_mul_f32 v[48:49], v[40:41], v[148:149]
	s_waitcnt vmcnt(4)
	v_lshlrev_b32_e32 v40, 16, v104
	v_and_b32_e32 v41, 0xffff0000, v104
	v_lshlrev_b32_e32 v42, 16, v105
	v_and_b32_e32 v43, 0xffff0000, v105
	v_lshlrev_b32_e32 v104, 16, v106
	v_and_b32_e32 v105, 0xffff0000, v106
	v_lshlrev_b32_e32 v106, 16, v107
	v_and_b32_e32 v107, 0xffff0000, v107
	v_pk_mul_f32 v[38:39], v[38:39], v[42:43]
	v_pk_mul_f32 v[36:37], v[36:37], v[40:41]
	v_pk_mul_f32 v[42:43], v[30:31], v[106:107]
	v_pk_mul_f32 v[40:41], v[28:29], v[104:105]
	s_waitcnt vmcnt(3)
	v_lshlrev_b32_e32 v28, 16, v140
	v_and_b32_e32 v29, 0xffff0000, v140
	v_lshlrev_b32_e32 v30, 16, v141
	v_and_b32_e32 v31, 0xffff0000, v141
	v_lshlrev_b32_e32 v104, 16, v142
	v_and_b32_e32 v105, 0xffff0000, v142
	v_lshlrev_b32_e32 v106, 16, v143
	v_and_b32_e32 v107, 0xffff0000, v143
	v_pk_mul_f32 v[30:31], v[34:35], v[30:31]
	v_pk_mul_f32 v[28:29], v[32:33], v[28:29]
	v_pk_mul_f32 v[34:35], v[26:27], v[106:107]
	v_pk_mul_f32 v[32:33], v[24:25], v[104:105]
	s_waitcnt vmcnt(2)
	v_lshlrev_b32_e32 v24, 16, v144
	v_and_b32_e32 v25, 0xffff0000, v144
	v_lshlrev_b32_e32 v26, 16, v145
	v_and_b32_e32 v27, 0xffff0000, v145
	v_lshlrev_b32_e32 v104, 16, v146
	v_and_b32_e32 v105, 0xffff0000, v146
	v_lshlrev_b32_e32 v106, 16, v147
	v_and_b32_e32 v107, 0xffff0000, v147
	v_pk_mul_f32 v[22:23], v[22:23], v[26:27]
	v_pk_mul_f32 v[20:21], v[20:21], v[24:25]
	v_pk_mul_f32 v[26:27], v[14:15], v[106:107]
	v_pk_mul_f32 v[24:25], v[12:13], v[104:105]
	s_waitcnt vmcnt(1)
	v_lshlrev_b32_e32 v12, 16, v80
	v_and_b32_e32 v13, 0xffff0000, v80
	v_lshlrev_b32_e32 v14, 16, v81
	v_and_b32_e32 v15, 0xffff0000, v81
	v_lshlrev_b32_e32 v80, 16, v82
	v_and_b32_e32 v81, 0xffff0000, v82
	v_lshlrev_b32_e32 v82, 16, v83
	v_and_b32_e32 v83, 0xffff0000, v83
	v_pk_mul_f32 v[14:15], v[18:19], v[14:15]
	v_pk_mul_f32 v[12:13], v[16:17], v[12:13]
	v_pk_mul_f32 v[10:11], v[10:11], v[82:83]
	v_pk_mul_f32 v[8:9], v[8:9], v[80:81]
	s_waitcnt vmcnt(0)
	v_lshlrev_b32_e32 v16, 16, v184
	v_and_b32_e32 v17, 0xffff0000, v184
	v_lshlrev_b32_e32 v18, 16, v185
	v_and_b32_e32 v19, 0xffff0000, v185
	v_lshlrev_b32_e32 v80, 16, v186
	v_and_b32_e32 v81, 0xffff0000, v186
	v_lshlrev_b32_e32 v82, 16, v187
	v_and_b32_e32 v83, 0xffff0000, v187
	v_pk_mul_f32 v[6:7], v[6:7], v[18:19]
	v_pk_mul_f32 v[4:5], v[4:5], v[16:17]
	v_pk_mul_f32 v[2:3], v[2:3], v[82:83]
	v_pk_mul_f32 v[0:1], v[0:1], v[80:81]

; __device__ __forceinline__ unsigned cvt_pk_bf16(float lo, float hi) { unsigned r; asm volatile("v_cvt_pk_bf16_f32 %0, %1, %2" : "=v"(r) : "v"(lo), "v"(hi)); return r; }
; __device__ __forceinline__ float bflo(unsigned w) { return __uint_as_float(w << 16); }
; __device__ __forceinline__ float bfhi(unsigned w) { return __uint_as_float(w & 0xffff0000u); }
;     __device__ __forceinline__ void scale(Acc& acc, const Unit& u, int wr, int wc, int fr, int fq, int pc, bool store) const {
;     ...
;         for (int ai = 0; ai < 2; ++ai) {
;             u32x4 g[4][2];
; #pragma unroll
;             for (int m = 0; m < 4; ++m) {
;                 const unsigned rowoff = (unsigned)(row0 + ai * HALF + m * 16) * (unsigned)(NIN * 2) + (unsigned)col0 * 2u;
; #pragma unroll
;                 for (int bj = 0; bj < 2; ++bj) g[m][bj] = *(const u32x4*)(Pb + (rowoff + (unsigned)((pc + bj * HALF) * 2)));
;             }
; #pragma unroll
;             for (int m = 0; m < 4; ++m) {
;                 const unsigned ooff = (unsigned)(row0 + ai * HALF + m * 16) * (unsigned)(ldo * 2) + (unsigned)col0 * 2u;
; #pragma unroll
;                 for (int bj = 0; bj < 2; ++bj) {
;                     const u32x4 gg = g[m][bj];
;                     const f32x4 s0 = (f32x4){bflo(gg.x), bfhi(gg.x), bflo(gg.y), bfhi(gg.y)}, s1 = (f32x4){bflo(gg.z), bfhi(gg.z), bflo(gg.w), bfhi(gg.w)};
;                     const f32x4 v0 = acc[ai][bj][m][0] * s0, v1 = acc[ai][bj][m][1] * s1;
;                     if (store) { u32x4 w; w.x = cvt_pk_bf16(v0[0], v0[1]); w.y = cvt_pk_bf16(v0[2], v0[3]); w.z = cvt_pk_bf16(v1[0], v1[1]); w.w = cvt_pk_bf16(v1[2], v1[3]); *(u32x4*)(Ob + (ooff + (unsigned)(bj * HALF * 2))) = w; }
;                     else { acc[ai][bj][m][0] = v0; acc[ai][bj][m][1] = v1; }
.LBB0_1355:
	s_andn2_b64 vcc, exec, s[2:3]
	v_lshlrev_b32_e32 v16, 1, v183
	v_mad_u64_u32 v[80:81], s[24:25], v182, s52, v[16:17]
	v_add_u32_e32 v17, 0x1a00, v80
	global_load_dwordx4 v[104:107], v17, s[68:69]
	v_add_u32_e32 v17, 0x1b00, v80
	global_load_dwordx4 v[140:143], v17, s[68:69]
	v_add_u32_e32 v17, 0x25a00, v80
	global_load_dwordx4 v[144:147], v17, s[68:69]
	v_add_u32_e32 v17, 0x25b00, v80
	global_load_dwordx4 v[148:151], v17, s[68:69]
	v_add_u32_e32 v17, 0x49a00, v80
	global_load_dwordx4 v[184:187], v17, s[68:69]
	v_lshl_add_u32 v81, v182, 12, v16
	v_add_u32_e32 v16, 0x49b00, v80
	v_add_u32_e32 v17, 0x6da00, v80
	v_add_u32_e32 v18, 0x6db00, v80
	global_load_dwordx4 v[180:183], v16, s[68:69]
	global_load_dwordx4 v[188:191], v17, s[68:69]
	s_nop 0
	global_load_dwordx4 v[16:19], v18, s[68:69]
	v_add_u32_e32 v206, 0x100, v81
	v_add_u32_e32 v207, 0x10000, v81
	s_mov_b64 s[2:3], -1
	s_waitcnt vmcnt(7)
	v_lshlrev_b32_e32 v192, 16, v106
	v_and_b32_e32 v193, 0xffff0000, v106
	v_lshlrev_b32_e32 v106, 16, v107
	v_and_b32_e32 v107, 0xffff0000, v107
	v_lshlrev_b32_e32 v82, 16, v104
	v_and_b32_e32 v83, 0xffff0000, v104
	v_lshlrev_b32_e32 v104, 16, v105
	v_and_b32_e32 v105, 0xffff0000, v105
	v_pk_mul_f32 v[134:135], v[134:135], v[106:107]
	v_pk_mul_f32 v[106:107], v[132:133], v[192:193]
	s_waitcnt vmcnt(6)
	v_lshlrev_b32_e32 v194, 16, v140
	v_and_b32_e32 v195, 0xffff0000, v140
	v_lshlrev_b32_e32 v140, 16, v141
	v_and_b32_e32 v141, 0xffff0000, v141
	v_lshlrev_b32_e32 v196, 16, v142
	v_and_b32_e32 v197, 0xffff0000, v142
	v_lshlrev_b32_e32 v142, 16, v143
	v_and_b32_e32 v143, 0xffff0000, v143
	v_pk_mul_f32 v[138:139], v[138:139], v[104:105]
	v_pk_mul_f32 v[82:83], v[136:137], v[82:83]
	s_waitcnt vmcnt(5)
	v_lshlrev_b32_e32 v198, 16, v144
	v_cvt_pk_bf16_f32 v104, v82, v83
	v_cvt_pk_bf16_f32 v105, v138, v139
	v_cvt_pk_bf16_f32 v106, v106, v107
	v_cvt_pk_bf16_f32 v107, v134, v135
	v_and_b32_e32 v199, 0xffff0000, v144
	v_lshlrev_b32_e32 v144, 16, v145
	v_and_b32_e32 v145, 0xffff0000, v145
	v_lshlrev_b32_e32 v200, 16, v146
	v_and_b32_e32 v201, 0xffff0000, v146
	v_lshlrev_b32_e32 v146, 16, v147
	v_and_b32_e32 v147, 0xffff0000, v147
	v_pk_mul_f32 v[126:127], v[126:127], v[140:141]
	v_pk_mul_f32 v[124:125], v[124:125], v[194:195]
	v_pk_mul_f32 v[122:123], v[122:123], v[142:143]
	v_pk_mul_f32 v[120:121], v[120:121], v[196:197]
	global_store_dwordx4 v81, v[104:107], s[72:73]
	s_waitcnt vmcnt(5)
	v_lshlrev_b32_e32 v202, 16, v148
	v_and_b32_e32 v203, 0xffff0000, v148
	v_cvt_pk_bf16_f32 v104, v124, v125
	v_cvt_pk_bf16_f32 v105, v126, v127
	v_cvt_pk_bf16_f32 v106, v120, v121
	v_cvt_pk_bf16_f32 v107, v122, v123
	v_lshlrev_b32_e32 v148, 16, v149
	v_and_b32_e32 v149, 0xffff0000, v149
	v_lshlrev_b32_e32 v204, 16, v150
	v_and_b32_e32 v205, 0xffff0000, v150
	v_lshlrev_b32_e32 v150, 16, v151
	v_and_b32_e32 v151, 0xffff0000, v151
	v_pk_mul_f32 v[130:131], v[130:131], v[144:145]
	v_pk_mul_f32 v[128:129], v[128:129], v[198:199]
	v_pk_mul_f32 v[118:119], v[118:119], v[146:147]
	v_pk_mul_f32 v[116:117], v[116:117], v[200:201]
	global_store_dwordx4 v206, v[104:107], s[72:73]
	v_pk_mul_f32 v[114:115], v[114:115], v[148:149]
	v_pk_mul_f32 v[112:113], v[112:113], v[202:203]
	v_cvt_pk_bf16_f32 v104, v128, v129
	v_cvt_pk_bf16_f32 v105, v130, v131
	v_cvt_pk_bf16_f32 v106, v116, v117
	v_cvt_pk_bf16_f32 v107, v118, v119
	v_pk_mul_f32 v[110:111], v[110:111], v[150:151]
	v_pk_mul_f32 v[108:109], v[108:109], v[204:205]
	global_store_dwordx4 v207, v[104:107], s[72:73]
	v_add_u32_e32 v82, 0x10100, v81
	s_waitcnt vmcnt(6)
	v_and_b32_e32 v83, 0xffff0000, v184
	v_cvt_pk_bf16_f32 v104, v112, v113
	v_cvt_pk_bf16_f32 v105, v114, v115
	v_cvt_pk_bf16_f32 v106, v108, v109
	v_cvt_pk_bf16_f32 v107, v110, v111
	global_store_dwordx4 v82, v[104:107], s[72:73]
	v_lshlrev_b32_e32 v82, 16, v184
	v_lshlrev_b32_e32 v108, 16, v187
	v_lshlrev_b32_e32 v106, 16, v186
	v_and_b32_e32 v107, 0xffff0000, v186
	v_and_b32_e32 v109, 0xffff0000, v187
	v_lshlrev_b32_e32 v104, 16, v185
	v_and_b32_e32 v105, 0xffff0000, v185
	v_pk_mul_f32 v[82:83], v[100:101], v[82:83]
	v_pk_mul_f32 v[100:101], v[98:99], v[108:109]
	v_pk_mul_f32 v[98:99], v[96:97], v[106:107]
	v_add_u32_e32 v110, 0x20000, v81
	v_pk_mul_f32 v[102:103], v[102:103], v[104:105]
	v_cvt_pk_bf16_f32 v96, v82, v83
	s_waitcnt vmcnt(6)
	v_lshlrev_b32_e32 v82, 16, v180
	v_cvt_pk_bf16_f32 v97, v102, v103
	v_cvt_pk_bf16_f32 v98, v98, v99
	v_cvt_pk_bf16_f32 v99, v100, v101
	global_store_dwordx4 v110, v[96:99], s[72:73]
	v_and_b32_e32 v83, 0xffff0000, v180
	v_lshlrev_b32_e32 v100, 16, v183
	v_lshlrev_b32_e32 v98, 16, v182
	v_and_b32_e32 v99, 0xffff0000, v182
	v_and_b32_e32 v101, 0xffff0000, v183
	v_lshlrev_b32_e32 v96, 16, v181
	v_and_b32_e32 v97, 0xffff0000, v181
	v_pk_mul_f32 v[82:83], v[92:93], v[82:83]
	v_pk_mul_f32 v[92:93], v[90:91], v[100:101]
	v_pk_mul_f32 v[90:91], v[88:89], v[98:99]
	v_pk_mul_f32 v[94:95], v[94:95], v[96:97]
	v_cvt_pk_bf16_f32 v88, v82, v83
	v_add_u32_e32 v82, 0x20100, v81
	v_cvt_pk_bf16_f32 v89, v94, v95
	v_cvt_pk_bf16_f32 v90, v90, v91
	v_cvt_pk_bf16_f32 v91, v92, v93
	global_store_dwordx4 v82, v[88:91], s[72:73]
	s_waitcnt vmcnt(7)
	v_lshlrev_b32_e32 v82, 16, v188
	v_and_b32_e32 v83, 0xffff0000, v188
	v_lshlrev_b32_e32 v90, 16, v190
	v_and_b32_e32 v91, 0xffff0000, v190
	v_lshlrev_b32_e32 v92, 16, v191
	v_and_b32_e32 v93, 0xffff0000, v191
	v_lshlrev_b32_e32 v88, 16, v189
	v_and_b32_e32 v89, 0xffff0000, v189
	v_pk_mul_f32 v[82:83], v[84:85], v[82:83]
	v_pk_mul_f32 v[84:85], v[78:79], v[92:93]
	v_pk_mul_f32 v[78:79], v[76:77], v[90:91]
	v_add_u32_e32 v94, 0x30000, v81
	v_pk_mul_f32 v[86:87], v[86:87], v[88:89]
	v_cvt_pk_bf16_f32 v76, v82, v83
	s_nop 0
	v_cvt_pk_bf16_f32 v77, v86, v87
	v_cvt_pk_bf16_f32 v78, v78, v79
	v_cvt_pk_bf16_f32 v79, v84, v85
	global_store_dwordx4 v94, v[76:79], s[72:73]
	s_nop 1
	s_waitcnt vmcnt(7)
; __device__ __forceinline__ unsigned cvt_pk_bf16(float lo, float hi) { unsigned r; asm volatile("v_cvt_pk_bf16_f32 %0, %1, %2" : "=v"(r) : "v"(lo), "v"(hi)); return r; }
; __device__ __forceinline__ float bflo(unsigned w) { return __uint_as_float(w << 16); }
;     __device__ __forceinline__ void scale(Acc& acc, const Unit& u, int wr, int wc, int fr, int fq, int pc, bool store) const {
;     ...
;         for (int ai = 0; ai < 2; ++ai) {
;             u32x4 g[4][2];
; #pragma unroll
;             for (int m = 0; m < 4; ++m) {
;                 const unsigned rowoff = (unsigned)(row0 + ai * HALF + m * 16) * (unsigned)(NIN * 2) + (unsigned)col0 * 2u;
; #pragma unroll
;                 for (int bj = 0; bj < 2; ++bj) g[m][bj] = *(const u32x4*)(Pb + (rowoff + (unsigned)((pc + bj * HALF) * 2)));
;             }
; #pragma unroll
;             for (int m = 0; m < 4; ++m) {
;                 const unsigned ooff = (unsigned)(row0 + ai * HALF + m * 16) * (unsigned)(ldo * 2) + (unsigned)col0 * 2u;
; #pragma unroll
;                 for (int bj = 0; bj < 2; ++bj) {
;                     const u32x4 gg = g[m][bj];
;                     const f32x4 s0 = (f32x4){bflo(gg.x), bfhi(gg.x), bflo(gg.y), bfhi(gg.y)}, s1 = (f32x4){bflo(gg.z), bfhi(gg.z), bflo(gg.w), bfhi(gg.w)};
;                     const f32x4 v0 = acc[ai][bj][m][0] * s0, v1 = acc[ai][bj][m][1] * s1;
;                     if (store) { u32x4 w; w.x = cvt_pk_bf16(v0[0], v0[1]); w.y = cvt_pk_bf16(v0[2], v0[3]); w.z = cvt_pk_bf16(v1[0], v1[1]); w.w = cvt_pk_bf16(v1[2], v1[3]); *(u32x4*)(Ob + (ooff + (unsigned)(bj * HALF * 2))) = w; }
;                     else { acc[ai][bj][m][0] = v0; acc[ai][bj][m][1] = v1; }
;                 }
;             }
;             asm volatile("" ::: "memory");
;         }
; template <class Epi, class Sched, bool ALIGN_EPI>
; __device__ __forceinline__ void gemm_phase(LAS unsigned char* lds, const Gemm g, const Sched& S, const Epi& E) {
;     ...
;         if (!has_next) break;
; #pragma unroll
;         for (int a = 0; a < 2; ++a)
; #pragma unroll
;             for (int b = 0; b < 2; ++b)
; #pragma unroll
;                 for (int m = 0; m < 4; ++m)
; #pragma unroll
;                     for (int n = 0; n < 2; ++n) acc[a][b][m][n] = (f32x4){0.f, 0.f, 0.f, 0.f};
;         cur = nxt; cA = nA; cB = nB; ++ui;
;         if constexpr (ALIGN_EPI) { if (wr == 1) PG8_BAR; }
	v_lshlrev_b32_e32 v76, 16, v16
	v_and_b32_e32 v77, 0xffff0000, v16
	v_lshlrev_b32_e32 v16, 16, v17
	v_and_b32_e32 v17, 0xffff0000, v17
	v_lshlrev_b32_e32 v78, 16, v18
	v_and_b32_e32 v79, 0xffff0000, v18
	v_lshlrev_b32_e32 v18, 16, v19
	v_and_b32_e32 v19, 0xffff0000, v19
	v_pk_mul_f32 v[74:75], v[74:75], v[16:17]
	v_pk_mul_f32 v[16:17], v[72:73], v[76:77]
	v_pk_mul_f32 v[70:71], v[70:71], v[18:19]
	v_pk_mul_f32 v[18:19], v[68:69], v[78:79]
	v_add_u32_e32 v68, 0x30100, v81
	v_cvt_pk_bf16_f32 v16, v16, v17
	v_cvt_pk_bf16_f32 v17, v74, v75
	v_cvt_pk_bf16_f32 v18, v18, v19
	v_cvt_pk_bf16_f32 v19, v70, v71
	global_store_dwordx4 v68, v[16:19], s[72:73]
	s_nop 1
	v_add_u32_e32 v16, 0x121a00, v80
	global_load_dwordx4 v[72:75], v16, s[68:69]
	v_add_u32_e32 v16, 0x121b00, v80
	global_load_dwordx4 v[76:79], v16, s[68:69]
	v_add_u32_e32 v16, 0x145a00, v80
	global_load_dwordx4 v[82:85], v16, s[68:69]
	v_add_u32_e32 v16, 0x145b00, v80
	global_load_dwordx4 v[86:89], v16, s[68:69]
	v_add_u32_e32 v16, 0x169a00, v80
	global_load_dwordx4 v[90:93], v16, s[68:69]
	v_add_u32_e32 v16, 0x169b00, v80
	global_load_dwordx4 v[94:97], v16, s[68:69]
	v_add_u32_e32 v16, 0x18da00, v80
	v_add_u32_e32 v17, 0x18db00, v80
	global_load_dwordx4 v[68:71], v16, s[68:69]
	s_nop 0
	global_load_dwordx4 v[16:19], v17, s[68:69]
	v_add_u32_e32 v80, 0x80000, v81
	s_waitcnt vmcnt(7)
	v_lshlrev_b32_e32 v98, 16, v72
	v_and_b32_e32 v99, 0xffff0000, v72
	v_lshlrev_b32_e32 v72, 16, v73
	v_and_b32_e32 v73, 0xffff0000, v73
	v_lshlrev_b32_e32 v100, 16, v74
	v_and_b32_e32 v101, 0xffff0000, v74
	v_lshlrev_b32_e32 v74, 16, v75
	v_and_b32_e32 v75, 0xffff0000, v75
	v_pk_mul_f32 v[62:63], v[62:63], v[72:73]
	v_pk_mul_f32 v[60:61], v[60:61], v[98:99]
	v_pk_mul_f32 v[66:67], v[66:67], v[74:75]
	v_pk_mul_f32 v[64:65], v[64:65], v[100:101]
	v_cvt_pk_bf16_f32 v60, v60, v61
	v_cvt_pk_bf16_f32 v61, v62, v63
	s_nop 0
	v_cvt_pk_bf16_f32 v62, v64, v65
	v_cvt_pk_bf16_f32 v63, v66, v67
	global_store_dwordx4 v80, v[60:63], s[72:73]
	s_waitcnt vmcnt(7)
	v_lshlrev_b32_e32 v64, 16, v78
	v_and_b32_e32 v65, 0xffff0000, v78
	v_lshlrev_b32_e32 v60, 16, v76
	v_and_b32_e32 v61, 0xffff0000, v76
	v_lshlrev_b32_e32 v62, 16, v77
	v_and_b32_e32 v63, 0xffff0000, v77
	v_lshlrev_b32_e32 v66, 16, v79
	v_and_b32_e32 v67, 0xffff0000, v79
	v_pk_mul_f32 v[54:55], v[54:55], v[62:63]
	v_pk_mul_f32 v[52:53], v[52:53], v[60:61]
	v_pk_mul_f32 v[56:57], v[56:57], v[64:65]
	v_pk_mul_f32 v[58:59], v[58:59], v[66:67]
	v_cvt_pk_bf16_f32 v52, v52, v53
	v_cvt_pk_bf16_f32 v53, v54, v55
	v_cvt_pk_bf16_f32 v54, v56, v57
	v_add_u32_e32 v56, 0x80100, v81
	v_cvt_pk_bf16_f32 v55, v58, v59
	global_store_dwordx4 v56, v[52:55], s[72:73]
	s_waitcnt vmcnt(7)
	v_lshlrev_b32_e32 v56, 16, v84
	v_and_b32_e32 v57, 0xffff0000, v84
	v_lshlrev_b32_e32 v52, 16, v82
	v_and_b32_e32 v53, 0xffff0000, v82
	v_lshlrev_b32_e32 v54, 16, v83
	v_and_b32_e32 v55, 0xffff0000, v83
	v_lshlrev_b32_e32 v58, 16, v85
	v_and_b32_e32 v59, 0xffff0000, v85
	v_pk_mul_f32 v[46:47], v[46:47], v[54:55]
	v_pk_mul_f32 v[44:45], v[44:45], v[52:53]
	v_add_u32_e32 v60, 0x90000, v81
	v_pk_mul_f32 v[50:51], v[50:51], v[58:59]
	v_pk_mul_f32 v[48:49], v[48:49], v[56:57]
	v_cvt_pk_bf16_f32 v44, v44, v45
	v_cvt_pk_bf16_f32 v45, v46, v47
	s_nop 0
	v_cvt_pk_bf16_f32 v46, v48, v49
	v_cvt_pk_bf16_f32 v47, v50, v51
	global_store_dwordx4 v60, v[44:47], s[72:73]
	s_waitcnt vmcnt(7)
	v_lshlrev_b32_e32 v48, 16, v88
	v_and_b32_e32 v49, 0xffff0000, v88
	v_lshlrev_b32_e32 v44, 16, v86
	v_and_b32_e32 v45, 0xffff0000, v86
	v_lshlrev_b32_e32 v46, 16, v87
	v_and_b32_e32 v47, 0xffff0000, v87
	v_lshlrev_b32_e32 v50, 16, v89
	v_and_b32_e32 v51, 0xffff0000, v89
	v_pk_mul_f32 v[38:39], v[38:39], v[46:47]
	v_pk_mul_f32 v[36:37], v[36:37], v[44:45]
	v_pk_mul_f32 v[40:41], v[40:41], v[48:49]
	v_pk_mul_f32 v[42:43], v[42:43], v[50:51]
	v_cvt_pk_bf16_f32 v36, v36, v37
	v_cvt_pk_bf16_f32 v37, v38, v39
	v_cvt_pk_bf16_f32 v38, v40, v41
	v_add_u32_e32 v40, 0x90100, v81
	v_cvt_pk_bf16_f32 v39, v42, v43
	global_store_dwordx4 v40, v[36:39], s[72:73]
	s_waitcnt vmcnt(7)
	v_lshlrev_b32_e32 v40, 16, v92
	v_and_b32_e32 v41, 0xffff0000, v92
	v_lshlrev_b32_e32 v36, 16, v90
	v_and_b32_e32 v37, 0xffff0000, v90
	v_lshlrev_b32_e32 v38, 16, v91
	v_and_b32_e32 v39, 0xffff0000, v91
	v_lshlrev_b32_e32 v42, 16, v93
	v_and_b32_e32 v43, 0xffff0000, v93
	v_pk_mul_f32 v[30:31], v[30:31], v[38:39]
	v_pk_mul_f32 v[28:29], v[28:29], v[36:37]
	v_add_u32_e32 v44, 0xa0000, v81
	v_pk_mul_f32 v[34:35], v[34:35], v[42:43]
	v_pk_mul_f32 v[32:33], v[32:33], v[40:41]
	v_cvt_pk_bf16_f32 v28, v28, v29
	v_cvt_pk_bf16_f32 v29, v30, v31
	s_nop 0
	v_cvt_pk_bf16_f32 v30, v32, v33
	v_cvt_pk_bf16_f32 v31, v34, v35
	global_store_dwordx4 v44, v[28:31], s[72:73]
	s_waitcnt vmcnt(7)
	v_lshlrev_b32_e32 v32, 16, v96
	v_and_b32_e32 v33, 0xffff0000, v96
	v_lshlrev_b32_e32 v28, 16, v94
	v_and_b32_e32 v29, 0xffff0000, v94
	v_lshlrev_b32_e32 v30, 16, v95
	v_and_b32_e32 v31, 0xffff0000, v95
	v_lshlrev_b32_e32 v34, 16, v97
	v_and_b32_e32 v35, 0xffff0000, v97
	v_pk_mul_f32 v[22:23], v[22:23], v[30:31]
	v_pk_mul_f32 v[20:21], v[20:21], v[28:29]
	v_pk_mul_f32 v[24:25], v[24:25], v[32:33]
	v_pk_mul_f32 v[26:27], v[26:27], v[34:35]
	v_cvt_pk_bf16_f32 v20, v20, v21
	v_cvt_pk_bf16_f32 v21, v22, v23
	v_cvt_pk_bf16_f32 v22, v24, v25
	v_add_u32_e32 v24, 0xa0100, v81
	v_cvt_pk_bf16_f32 v23, v26, v27
	global_store_dwordx4 v24, v[20:23], s[72:73]
	s_waitcnt vmcnt(7)
	v_lshlrev_b32_e32 v24, 16, v70
	v_and_b32_e32 v25, 0xffff0000, v70
	v_lshlrev_b32_e32 v20, 16, v68
	v_and_b32_e32 v21, 0xffff0000, v68
	v_lshlrev_b32_e32 v22, 16, v69
	v_and_b32_e32 v23, 0xffff0000, v69
	v_lshlrev_b32_e32 v26, 16, v71
	v_and_b32_e32 v27, 0xffff0000, v71
	v_add_u32_e32 v28, 0xb0000, v81
	v_pk_mul_f32 v[14:15], v[14:15], v[22:23]
	v_pk_mul_f32 v[12:13], v[12:13], v[20:21]
	v_pk_mul_f32 v[20:21], v[10:11], v[26:27]
	v_pk_mul_f32 v[10:11], v[8:9], v[24:25]
	v_cvt_pk_bf16_f32 v8, v12, v13
	v_cvt_pk_bf16_f32 v9, v14, v15
	s_waitcnt vmcnt(6)
	v_lshlrev_b32_e32 v12, 16, v18
	v_cvt_pk_bf16_f32 v10, v10, v11
	v_cvt_pk_bf16_f32 v11, v20, v21
	global_store_dwordx4 v28, v[8:11], s[72:73]
	v_and_b32_e32 v13, 0xffff0000, v18
	v_lshlrev_b32_e32 v14, 16, v19
	v_lshlrev_b32_e32 v8, 16, v16
	v_and_b32_e32 v9, 0xffff0000, v16
	v_and_b32_e32 v15, 0xffff0000, v19
	v_pk_mul_f32 v[4:5], v[4:5], v[8:9]
	v_lshlrev_b32_e32 v10, 16, v17
	v_and_b32_e32 v11, 0xffff0000, v17
	v_pk_mul_f32 v[8:9], v[2:3], v[14:15]
	v_pk_mul_f32 v[2:3], v[0:1], v[12:13]
	v_cvt_pk_bf16_f32 v0, v4, v5
	v_add_u32_e32 v4, 0xb0100, v81
	v_pk_mul_f32 v[6:7], v[6:7], v[10:11]
	s_nop 0
	v_cvt_pk_bf16_f32 v1, v6, v7
	v_cvt_pk_bf16_f32 v2, v2, v3
	v_cvt_pk_bf16_f32 v3, v8, v9
	global_store_dwordx4 v4, v[0:3], s[72:73]
	s_cbranch_vccnz .LBB0_1342
	s_andn2_b64 vcc, exec, s[4:5]
	s_cbranch_vccnz .LBB0_1341
	s_barrier
	s_branch .LBB0_1341
